# scan producer: wait for next-next group's loads and pack them after the ring barrier instead of before it
# speedup vs baseline: 1.0581x; 1.0028x over previous
.LBB0_1899:
	s_cmpk_eq_i32 s80, 0x20c0
	s_waitcnt lgkmcnt(0)
	s_barrier
	s_waitcnt vmcnt(41)
	v_perm_b32 v95, v70, v49, s78
	s_waitcnt vmcnt(29)
	v_perm_b32 v90, v43, v54, s78
	s_waitcnt vmcnt(17)
	v_perm_b32 v83, v26, v36, s78
	s_waitcnt vmcnt(5)
	v_perm_b32 v25, v13, v19, s78
	v_perm_b32 v96, v74, v55, s78
	v_perm_b32 v91, v48, v68, s78
	v_perm_b32 v86, v31, v41, s78
	s_waitcnt vmcnt(4)
	v_perm_b32 v30, v17, v23, s78
	v_perm_b32 v97, v72, v52, s78
	v_perm_b32 v92, v46, v59, s78
	v_perm_b32 v87, v29, v40, s78
	s_waitcnt vmcnt(3)
	v_perm_b32 v32, v16, v22, s78
	v_perm_b32 v99, v78, v67, s78
	v_perm_b32 v94, v50, v69, s78
	v_perm_b32 v89, v33, v42, s78
	s_waitcnt vmcnt(2)
	v_perm_b32 v37, v18, v24, s78
	v_perm_b32 v98, v71, v51, s78
	v_perm_b32 v93, v44, v56, s78
	v_perm_b32 v88, v28, v39, s78
	s_waitcnt vmcnt(1)
	v_perm_b32 v34, v15, v21, s78
	s_cbranch_scc1 .LBB0_1901
	s_mov_b32 s61, s80
	v_mov_b32_e32 v85, v53
	v_mov_b32_e32 v82, v73
	v_mov_b32_e32 v81, v58
	v_mov_b32_e32 v80, v45
	v_mov_b32_e32 v76, v38
	v_mov_b32_e32 v57, v27
	v_mov_b32_e32 v47, v20
	s_waitcnt vmcnt(0)
	v_mov_b32_e32 v35, v14
	s_branch .LBB0_1675
